# mem/dilated attention softmax: permlane32_swap row max + deferred (threshold 8) accumulator rescale
# speedup vs baseline: 1.0259x; 1.0014x over previous
; #define LAS __attribute__((address_space(3)))
; #define MFMA32(a, b, c) __builtin_amdgcn_mfma_f32_32x32x16_bf16((a), (b), (c), 0, 0, 0)
; template <int D, int NM, int KSTR, int VSTR, bool QLDS, class BF> ...
;     ...
;         const LAS unsigned char* Kb = (m == 0 ? K0 : K1) + (32 * kk + r) * KSTR + h * 16;
;         v16f S;
; #pragma unroll
;         for (int i = 0; i < 16; ++i) S[i] = 0.f;
;         v8s kfa[D / 16];
; #pragma unroll
;         for (int ks = 0; ks < D / 16; ++ks) kfa[ks] = *(const LAS v8s*)(Kb + ks * 32);
;         __builtin_amdgcn_sched_barrier(0);
; #pragma unroll
;         for (int ks = 0; ks < D / 16; ++ks) { const v8s qf = QLDS ? *(const LAS v8s*)(qlds + (m * (D / 16) + ks) * 1024) : Q[m][ks]; S = MFMA32(kfa[ks], qf, S); }
;         __builtin_amdgcn_sched_barrier(0);
;         float tmax = NEGBIG;
; #pragma unroll
;         for (int i = 0; i < 16; ++i) { S[i] = S[i] * c1 + bias(i); tmax = fmaxf(tmax, S[i]); }
;         tmax = fmaxf(tmax, __shfl_xor(tmax, 32));
;         const float mo = st.m[m], mn = fmaxf(mo, tmax);
;         if (__any(mn > mo)) {
;             const float alpha = __builtin_amdgcn_exp2f(mo - mn);
;             st.l[m] *= alpha;
; #pragma unroll
;             for (int eb = 0; eb < 4; ++eb)
; #pragma unroll
;                 for (int i = 0; i < 16; ++i) st.O[m][eb][i] *= alpha;
;             st.m[m] = mn;
;         }
; __device__ __forceinline__ void dil_item(const Params& p, LAS unsigned char* lds, const int bitem) {
;     ...
;                 const int js = j0 + 32 * kk;
;                 if (js + 31 >= jq0 - 64 && js <= jq0 + 31 + 64) {
;                     const BiasBand bf{tab, js + 4 * h - jq};
.LBB0_172:
	s_and_saveexec_b64 s[18:19], s[10:11]
	s_cbranch_execz .LBB0_165
	v_subrev_u32_e32 v67, 33, v176
	v_cmp_ge_i32_e32 vcc, v67, v188
	v_cmp_le_i32_e64 s[38:39], v66, v189
	s_and_b64 s[10:11], vcc, s[38:39]
	s_and_saveexec_b64 s[20:21], s[10:11]
	s_cbranch_execz .LBB0_209
	v_add_u32_e32 v70, v190, v187
	ds_read_b128 v[66:69], v70
	ds_read_b128 v[198:201], v70 offset:32
	ds_read_b128 v[216:219], v70 offset:64
	ds_read_b128 v[220:223], v70 offset:96
	ds_read_b128 v[224:227], v70 offset:128
	ds_read_b128 v[228:231], v70 offset:160
	ds_read_b128 v[232:235], v70 offset:192
	ds_read_b128 v[236:239], v70 offset:224
	v_lshl_add_u64 v[178:179], v[174:175], 0, s[6:7]
	v_subrev_u32_e32 v197, 64, v178
	s_waitcnt lgkmcnt(7)
	v_mfma_f32_32x32x16_bf16 v[66:81], v[66:69], v[82:85], 0
	s_waitcnt lgkmcnt(6)
	v_mfma_f32_32x32x16_bf16 v[66:81], v[198:201], v[86:89], v[66:81]
	s_waitcnt lgkmcnt(5)
	v_mfma_f32_32x32x16_bf16 v[66:81], v[216:219], v[90:93], v[66:81]
	s_waitcnt lgkmcnt(4)
	v_mfma_f32_32x32x16_bf16 v[66:81], v[220:223], v[94:97], v[66:81]
	s_waitcnt lgkmcnt(3)
	v_mfma_f32_32x32x16_bf16 v[66:81], v[224:227], v[98:101], v[66:81]
	s_waitcnt lgkmcnt(2)
	v_mfma_f32_32x32x16_bf16 v[66:81], v[228:231], v[102:105], v[66:81]
	s_waitcnt lgkmcnt(1)
	v_mfma_f32_32x32x16_bf16 v[66:81], v[232:235], v[106:109], v[66:81]
	s_waitcnt lgkmcnt(0)
	v_mfma_f32_32x32x16_bf16 v[66:81], v[236:239], v[110:113], v[66:81]
	v_lshl_add_u32 v178, v197, 2, v147
	ds_read_b32 v179, v178 offset:256
	ds_read_b32 v177, v178 offset:260
	ds_read_b32 v198, v178 offset:264
	ds_read_b32 v197, v178 offset:268
	ds_read_b32 v200, v178 offset:288
	ds_read_b32 v199, v178 offset:292
	ds_read_b32 v202, v178 offset:296
	ds_read_b32 v201, v178 offset:300
	s_waitcnt lgkmcnt(4)
	ds_read_b32 v215, v178 offset:320
	ds_read_b32 v203, v178 offset:324
	ds_read_b32 v217, v178 offset:328
	ds_read_b32 v216, v178 offset:332
	ds_read_b32 v219, v178 offset:352
	ds_read_b32 v218, v178 offset:356
	ds_read_b32 v221, v178 offset:360
	ds_read_b32 v220, v178 offset:364
	s_waitcnt lgkmcnt(0)
	v_fmac_f32_e32 v179, 0x3e0293ee, v66
	v_fmac_f32_e32 v177, 0x3e0293ee, v67
	v_max3_f32 v66, v179, s15, v177
	v_fmac_f32_e32 v198, 0x3e0293ee, v68
	v_fmac_f32_e32 v197, 0x3e0293ee, v69
	v_max3_f32 v66, v66, v198, v197
	v_fmac_f32_e32 v200, 0x3e0293ee, v70
	v_fmac_f32_e32 v199, 0x3e0293ee, v71
	v_max3_f32 v66, v66, v200, v199
	v_fmac_f32_e32 v202, 0x3e0293ee, v72
	v_fmac_f32_e32 v201, 0x3e0293ee, v73
	v_max3_f32 v66, v66, v202, v201
	v_fmac_f32_e32 v215, 0x3e0293ee, v74
	v_fmac_f32_e32 v203, 0x3e0293ee, v75
	v_max3_f32 v66, v66, v215, v203
	v_fmac_f32_e32 v217, 0x3e0293ee, v76
	v_fmac_f32_e32 v216, 0x3e0293ee, v77
	v_max3_f32 v66, v66, v217, v216
	v_fmac_f32_e32 v219, 0x3e0293ee, v78
	v_fmac_f32_e32 v218, 0x3e0293ee, v79
	v_max3_f32 v66, v66, v219, v218
	v_fmac_f32_e32 v221, 0x3e0293ee, v80
	v_fmac_f32_e32 v220, 0x3e0293ee, v81
	v_max3_f32 v66, v66, v221, v220
	v_mov_b32_e32 v67, v66
	s_nop 1
	v_permlane32_swap_b32_e32 v67, v66
	v_max_f32_e32 v66, v66, v67
	v_add_f32_e32 v67, 0x41000000, v193
	v_cmp_gt_f32_e32 vcc, v66, v67
	s_nop 1
	v_cndmask_b32_e32 v66, v193, v66, vcc
	s_cbranch_vccz .LBB0_208
	v_sub_f32_e32 v67, v193, v66
	v_exp_f32_e32 v68, v67
	v_mov_b32_e32 v193, v66
	v_mul_f32_e32 v194, v194, v68
	v_pk_mul_f32 v[64:65], v[64:65], v[68:69] op_sel_hi:[1,0]
	v_pk_mul_f32 v[62:63], v[62:63], v[68:69] op_sel_hi:[1,0]
	v_pk_mul_f32 v[60:61], v[60:61], v[68:69] op_sel_hi:[1,0]
	v_pk_mul_f32 v[58:59], v[58:59], v[68:69] op_sel_hi:[1,0]
	v_pk_mul_f32 v[56:57], v[56:57], v[68:69] op_sel_hi:[1,0]
	v_pk_mul_f32 v[54:55], v[54:55], v[68:69] op_sel_hi:[1,0]
	v_pk_mul_f32 v[52:53], v[52:53], v[68:69] op_sel_hi:[1,0]
	v_pk_mul_f32 v[50:51], v[50:51], v[68:69] op_sel_hi:[1,0]
	v_pk_mul_f32 v[48:49], v[48:49], v[68:69] op_sel_hi:[1,0]
	v_pk_mul_f32 v[46:47], v[46:47], v[68:69] op_sel_hi:[1,0]
	v_pk_mul_f32 v[44:45], v[44:45], v[68:69] op_sel_hi:[1,0]
	v_pk_mul_f32 v[42:43], v[42:43], v[68:69] op_sel_hi:[1,0]
	v_pk_mul_f32 v[40:41], v[40:41], v[68:69] op_sel_hi:[1,0]
	v_pk_mul_f32 v[38:39], v[38:39], v[68:69] op_sel_hi:[1,0]
	v_pk_mul_f32 v[36:37], v[36:37], v[68:69] op_sel_hi:[1,0]
	v_pk_mul_f32 v[34:35], v[34:35], v[68:69] op_sel_hi:[1,0]
	v_pk_mul_f32 v[32:33], v[32:33], v[68:69] op_sel_hi:[1,0]
	v_pk_mul_f32 v[30:31], v[30:31], v[68:69] op_sel_hi:[1,0]
	v_pk_mul_f32 v[28:29], v[28:29], v[68:69] op_sel_hi:[1,0]
	v_pk_mul_f32 v[26:27], v[26:27], v[68:69] op_sel_hi:[1,0]
	v_pk_mul_f32 v[24:25], v[24:25], v[68:69] op_sel_hi:[1,0]
	v_pk_mul_f32 v[22:23], v[22:23], v[68:69] op_sel_hi:[1,0]
	v_pk_mul_f32 v[20:21], v[20:21], v[68:69] op_sel_hi:[1,0]
	v_pk_mul_f32 v[18:19], v[18:19], v[68:69] op_sel_hi:[1,0]
	v_pk_mul_f32 v[16:17], v[16:17], v[68:69] op_sel_hi:[1,0]
	v_pk_mul_f32 v[14:15], v[14:15], v[68:69] op_sel_hi:[1,0]
	v_pk_mul_f32 v[12:13], v[12:13], v[68:69] op_sel_hi:[1,0]
	v_pk_mul_f32 v[10:11], v[10:11], v[68:69] op_sel_hi:[1,0]
	v_pk_mul_f32 v[8:9], v[8:9], v[68:69] op_sel_hi:[1,0]
	v_pk_mul_f32 v[6:7], v[6:7], v[68:69] op_sel_hi:[1,0]
	v_pk_mul_f32 v[4:5], v[4:5], v[68:69] op_sel_hi:[1,0]
	v_pk_mul_f32 v[2:3], v[2:3], v[68:69] op_sel_hi:[1,0]

; #define LAS __attribute__((address_space(3)))
; #define MFMA32(a, b, c) __builtin_amdgcn_mfma_f32_32x32x16_bf16((a), (b), (c), 0, 0, 0)
; template <int D, int NM, int KSTR, int VSTR, bool QLDS, class BF> ...
;     ...
;         const LAS unsigned char* Kb = (m == 0 ? K0 : K1) + (32 * kk + r) * KSTR + h * 16;
;         v16f S;
; #pragma unroll
;         for (int i = 0; i < 16; ++i) S[i] = 0.f;
;         v8s kfa[D / 16];
; #pragma unroll
;         for (int ks = 0; ks < D / 16; ++ks) kfa[ks] = *(const LAS v8s*)(Kb + ks * 32);
;         __builtin_amdgcn_sched_barrier(0);
; #pragma unroll
;         for (int ks = 0; ks < D / 16; ++ks) { const v8s qf = QLDS ? *(const LAS v8s*)(qlds + (m * (D / 16) + ks) * 1024) : Q[m][ks]; S = MFMA32(kfa[ks], qf, S); }
;         __builtin_amdgcn_sched_barrier(0);
;         float tmax = NEGBIG;
; #pragma unroll
;         for (int i = 0; i < 16; ++i) { S[i] = S[i] * c1 + bias(i); tmax = fmaxf(tmax, S[i]); }
;         tmax = fmaxf(tmax, __shfl_xor(tmax, 32));
;         const float mo = st.m[m], mn = fmaxf(mo, tmax);
;         if (__any(mn > mo)) {
;             const float alpha = __builtin_amdgcn_exp2f(mo - mn);
;             st.l[m] *= alpha;
; #pragma unroll
;             for (int eb = 0; eb < 4; ++eb)
; #pragma unroll
;                 for (int i = 0; i < 16; ++i) st.O[m][eb][i] *= alpha;
;             st.m[m] = mn;
;         }
; __device__ __forceinline__ void dil_item(const Params& p, LAS unsigned char* lds, const int bitem) {
;     ...
;                 const int js = j0 + 32 * kk;
;                 if (js + 31 >= jq0 - 64 && js <= jq0 + 31 + 64) {
;                     const BiasBand bf{tab, js + 4 * h - jq};
.LBB0_209:
	s_or_b64 exec, exec, s[20:21]
	v_subrev_u32_e32 v66, 32, v176
	v_add_u32_e32 v67, -1, v176
	v_cmp_ge_i32_e32 vcc, v67, v188
	v_cmp_le_i32_e64 s[38:39], v66, v189
	s_and_b64 s[10:11], vcc, s[38:39]
	s_and_saveexec_b64 s[20:21], s[10:11]
	s_cbranch_execz .LBB0_164
	v_add_u32_e32 v70, v190, v187
	ds_read_b128 v[66:69], v70 offset:8704
	ds_read_b128 v[198:201], v70 offset:8736
	ds_read_b128 v[216:219], v70 offset:8768
	ds_read_b128 v[220:223], v70 offset:8800
	ds_read_b128 v[224:227], v70 offset:8832
	ds_read_b128 v[228:231], v70 offset:8864
	ds_read_b128 v[232:235], v70 offset:8896
	ds_read_b128 v[236:239], v70 offset:8928
	v_lshl_add_u64 v[176:177], v[174:175], 0, s[6:7]
	v_subrev_u32_e32 v179, 32, v176
	s_waitcnt lgkmcnt(7)
	v_mfma_f32_32x32x16_bf16 v[66:81], v[66:69], v[82:85], 0
	s_waitcnt lgkmcnt(6)
	v_mfma_f32_32x32x16_bf16 v[66:81], v[198:201], v[86:89], v[66:81]
	s_waitcnt lgkmcnt(5)
	v_mfma_f32_32x32x16_bf16 v[66:81], v[216:219], v[90:93], v[66:81]
	s_waitcnt lgkmcnt(4)
	v_mfma_f32_32x32x16_bf16 v[66:81], v[220:223], v[94:97], v[66:81]
	s_waitcnt lgkmcnt(3)
	v_mfma_f32_32x32x16_bf16 v[66:81], v[224:227], v[98:101], v[66:81]
	s_waitcnt lgkmcnt(2)
	v_mfma_f32_32x32x16_bf16 v[66:81], v[228:231], v[102:105], v[66:81]
	s_waitcnt lgkmcnt(1)
	v_mfma_f32_32x32x16_bf16 v[66:81], v[232:235], v[106:109], v[66:81]
	s_waitcnt lgkmcnt(0)
	v_mfma_f32_32x32x16_bf16 v[66:81], v[236:239], v[110:113], v[66:81]
	v_lshl_add_u32 v176, v179, 2, v147
	ds_read_b32 v178, v176 offset:256
	ds_read_b32 v177, v176 offset:260
	ds_read_b32 v197, v176 offset:264
	ds_read_b32 v179, v176 offset:268
	ds_read_b32 v199, v176 offset:288
	ds_read_b32 v198, v176 offset:292
	ds_read_b32 v201, v176 offset:296
	ds_read_b32 v200, v176 offset:300
	s_waitcnt lgkmcnt(4)
	ds_read_b32 v203, v176 offset:320
	ds_read_b32 v202, v176 offset:324
	ds_read_b32 v216, v176 offset:328
	ds_read_b32 v215, v176 offset:332
	ds_read_b32 v218, v176 offset:352
	ds_read_b32 v217, v176 offset:356
	ds_read_b32 v220, v176 offset:360
	ds_read_b32 v219, v176 offset:364
	s_waitcnt lgkmcnt(0)
	v_fmac_f32_e32 v178, 0x3e0293ee, v66
	v_fmac_f32_e32 v177, 0x3e0293ee, v67
	v_max3_f32 v66, v178, s15, v177
	v_fmac_f32_e32 v197, 0x3e0293ee, v68
	v_fmac_f32_e32 v179, 0x3e0293ee, v69
	v_max3_f32 v66, v66, v197, v179
	v_fmac_f32_e32 v199, 0x3e0293ee, v70
	v_fmac_f32_e32 v198, 0x3e0293ee, v71
	v_max3_f32 v66, v66, v199, v198
	v_fmac_f32_e32 v201, 0x3e0293ee, v72
	v_fmac_f32_e32 v200, 0x3e0293ee, v73
	v_max3_f32 v66, v66, v201, v200
	v_fmac_f32_e32 v203, 0x3e0293ee, v74
	v_fmac_f32_e32 v202, 0x3e0293ee, v75
	v_max3_f32 v66, v66, v203, v202
	v_fmac_f32_e32 v216, 0x3e0293ee, v76
	v_fmac_f32_e32 v215, 0x3e0293ee, v77
	v_max3_f32 v66, v66, v216, v215
	v_fmac_f32_e32 v218, 0x3e0293ee, v78
	v_fmac_f32_e32 v217, 0x3e0293ee, v79
	v_max3_f32 v66, v66, v218, v217
	v_fmac_f32_e32 v220, 0x3e0293ee, v80
	v_fmac_f32_e32 v219, 0x3e0293ee, v81
	v_max3_f32 v66, v66, v220, v219
	v_mov_b32_e32 v67, v66
	s_nop 1
	v_permlane32_swap_b32_e32 v67, v66
	v_max_f32_e32 v66, v66, v67
	v_add_f32_e32 v67, 0x41000000, v193
	v_cmp_gt_f32_e32 vcc, v66, v67
	s_nop 1
	v_cndmask_b32_e32 v66, v193, v66, vcc
	s_cbranch_vccz .LBB0_163
	v_sub_f32_e32 v67, v193, v66
	v_exp_f32_e32 v68, v67
	v_mov_b32_e32 v193, v66
	v_mul_f32_e32 v194, v194, v68
	v_pk_mul_f32 v[64:65], v[64:65], v[68:69] op_sel_hi:[1,0]
	v_pk_mul_f32 v[62:63], v[62:63], v[68:69] op_sel_hi:[1,0]
	v_pk_mul_f32 v[60:61], v[60:61], v[68:69] op_sel_hi:[1,0]
	v_pk_mul_f32 v[58:59], v[58:59], v[68:69] op_sel_hi:[1,0]
	v_pk_mul_f32 v[56:57], v[56:57], v[68:69] op_sel_hi:[1,0]
	v_pk_mul_f32 v[54:55], v[54:55], v[68:69] op_sel_hi:[1,0]
	v_pk_mul_f32 v[52:53], v[52:53], v[68:69] op_sel_hi:[1,0]
	v_pk_mul_f32 v[50:51], v[50:51], v[68:69] op_sel_hi:[1,0]
	v_pk_mul_f32 v[48:49], v[48:49], v[68:69] op_sel_hi:[1,0]
	v_pk_mul_f32 v[46:47], v[46:47], v[68:69] op_sel_hi:[1,0]
	v_pk_mul_f32 v[44:45], v[44:45], v[68:69] op_sel_hi:[1,0]
	v_pk_mul_f32 v[42:43], v[42:43], v[68:69] op_sel_hi:[1,0]
	v_pk_mul_f32 v[40:41], v[40:41], v[68:69] op_sel_hi:[1,0]
	v_pk_mul_f32 v[38:39], v[38:39], v[68:69] op_sel_hi:[1,0]
	v_pk_mul_f32 v[36:37], v[36:37], v[68:69] op_sel_hi:[1,0]
	v_pk_mul_f32 v[34:35], v[34:35], v[68:69] op_sel_hi:[1,0]
	v_pk_mul_f32 v[32:33], v[32:33], v[68:69] op_sel_hi:[1,0]
	v_pk_mul_f32 v[30:31], v[30:31], v[68:69] op_sel_hi:[1,0]
	v_pk_mul_f32 v[28:29], v[28:29], v[68:69] op_sel_hi:[1,0]
	v_pk_mul_f32 v[26:27], v[26:27], v[68:69] op_sel_hi:[1,0]
	v_pk_mul_f32 v[24:25], v[24:25], v[68:69] op_sel_hi:[1,0]
	v_pk_mul_f32 v[22:23], v[22:23], v[68:69] op_sel_hi:[1,0]
	v_pk_mul_f32 v[20:21], v[20:21], v[68:69] op_sel_hi:[1,0]
	v_pk_mul_f32 v[18:19], v[18:19], v[68:69] op_sel_hi:[1,0]
	v_pk_mul_f32 v[16:17], v[16:17], v[68:69] op_sel_hi:[1,0]
	v_pk_mul_f32 v[14:15], v[14:15], v[68:69] op_sel_hi:[1,0]
	v_pk_mul_f32 v[12:13], v[12:13], v[68:69] op_sel_hi:[1,0]
	v_pk_mul_f32 v[10:11], v[10:11], v[68:69] op_sel_hi:[1,0]
	v_pk_mul_f32 v[8:9], v[8:9], v[68:69] op_sel_hi:[1,0]
	v_pk_mul_f32 v[6:7], v[6:7], v[68:69] op_sel_hi:[1,0]
	v_pk_mul_f32 v[4:5], v[4:5], v[68:69] op_sel_hi:[1,0]
	v_pk_mul_f32 v[2:3], v[2:3], v[68:69] op_sel_hi:[1,0]
	s_branch .LBB0_163

; #define LAS __attribute__((address_space(3)))
; #define MFMA32(a, b, c) __builtin_amdgcn_mfma_f32_32x32x16_bf16((a), (b), (c), 0, 0, 0)
; template <int D, int NM, int KSTR, int VSTR, bool QLDS, class BF> ...
;     ...
;         const LAS unsigned char* Kb = (m == 0 ? K0 : K1) + (32 * kk + r) * KSTR + h * 16;
;         v16f S;
; #pragma unroll
;         for (int i = 0; i < 16; ++i) S[i] = 0.f;
;         v8s kfa[D / 16];
; #pragma unroll
;         for (int ks = 0; ks < D / 16; ++ks) kfa[ks] = *(const LAS v8s*)(Kb + ks * 32);
;         __builtin_amdgcn_sched_barrier(0);
; #pragma unroll
;         for (int ks = 0; ks < D / 16; ++ks) { const v8s qf = QLDS ? *(const LAS v8s*)(qlds + (m * (D / 16) + ks) * 1024) : Q[m][ks]; S = MFMA32(kfa[ks], qf, S); }
;         __builtin_amdgcn_sched_barrier(0);
;         float tmax = NEGBIG;
; #pragma unroll
;         for (int i = 0; i < 16; ++i) { S[i] = S[i] * c1 + bias(i); tmax = fmaxf(tmax, S[i]); }
;         tmax = fmaxf(tmax, __shfl_xor(tmax, 32));
;         const float mo = st.m[m], mn = fmaxf(mo, tmax);
;         if (__any(mn > mo)) {
;             const float alpha = __builtin_amdgcn_exp2f(mo - mn);
;             st.l[m] *= alpha;
; #pragma unroll
;             for (int eb = 0; eb < 4; ++eb)
; #pragma unroll
;                 for (int i = 0; i < 16; ++i) st.O[m][eb][i] *= alpha;
;             st.m[m] = mn;
;         }
; __device__ __forceinline__ void mem_item(const Params& p, LAS unsigned char* lds, const int item, const int layer) {
;     ...
;         __syncthreads();
;         *(LAS v4u*)dK = g0; *(LAS v4u*)(dK + 32 * 272) = g1; *(LAS v4u*)dV = g2; *(LAS v4u*)(dV + 32 * 320) = g3;
;         __syncthreads();
;         if (t + 1 < 4) { const bf16* nK = sK + (size_t)(t + 1) * 64 * 1024;
;             g0 = *(const v4u*)nK; g1 = *(const v4u*)(nK + 32 * 1024); g2 = *(const v4u*)(nK + 512); g3 = *(const v4u*)(nK + 32 * 1024 + 512); }
.LBB0_249:
	v_lshl_add_u64 v[66:67], v[138:139], 0, s[6:7]
	s_mov_b32 s11, 0x9820000
	v_add_co_u32_e32 v68, vcc, s11, v66
	s_mov_b32 s11, 0x9830000
	s_nop 0
	v_addc_co_u32_e32 v69, vcc, 0, v67, vcc
	v_add_u32_e32 v0, v136, v134
	v_add_co_u32_e32 v66, vcc, s11, v66
	s_barrier
	s_waitcnt vmcnt(3)
	ds_write_b128 v0, v[114:117]
	s_waitcnt vmcnt(1)
	ds_write_b128 v0, v[126:129] offset:8704
	ds_write_b128 v146, v[118:121] offset:17408
	s_waitcnt vmcnt(0)
	ds_write_b128 v146, v[122:125] offset:27648
	s_waitcnt lgkmcnt(0)
	s_barrier
	v_addc_co_u32_e32 v67, vcc, 0, v67, vcc
	global_load_dwordx4 v[114:117], v[68:69], off
	global_load_dwordx4 v[118:121], v[68:69], off offset:1024
	global_load_dwordx4 v[126:129], v[66:67], off
	global_load_dwordx4 v[122:125], v[66:67], off offset:1024
	ds_read_b128 v[66:69], v144
	ds_read_b128 v[148:151], v144 offset:32
	ds_read_b128 v[152:155], v144 offset:64
	ds_read_b128 v[156:159], v144 offset:96
	ds_read_b128 v[160:163], v144 offset:128
	ds_read_b128 v[174:177], v144 offset:160
	ds_read_b128 v[178:181], v144 offset:192
	ds_read_b128 v[182:185], v144 offset:224
	s_waitcnt lgkmcnt(7)
	v_mfma_f32_32x32x16_bf16 v[66:81], v[66:69], v[110:113], 0
	s_waitcnt lgkmcnt(6)
	v_mfma_f32_32x32x16_bf16 v[66:81], v[148:151], v[106:109], v[66:81]
	s_waitcnt lgkmcnt(5)
	v_mfma_f32_32x32x16_bf16 v[66:81], v[152:155], v[102:105], v[66:81]
	s_waitcnt lgkmcnt(4)
	v_mfma_f32_32x32x16_bf16 v[66:81], v[156:159], v[98:101], v[66:81]
	s_waitcnt lgkmcnt(3)
	v_mfma_f32_32x32x16_bf16 v[66:81], v[160:163], v[94:97], v[66:81]
	s_waitcnt lgkmcnt(2)
	v_mfma_f32_32x32x16_bf16 v[66:81], v[174:177], v[90:93], v[66:81]
	s_waitcnt lgkmcnt(1)
	v_mfma_f32_32x32x16_bf16 v[66:81], v[178:181], v[86:89], v[66:81]
	s_waitcnt lgkmcnt(0)
	v_mfma_f32_32x32x16_bf16 v[66:81], v[182:185], v[82:85], v[66:81]
	s_nop 11
	v_fma_f32 v155, v66, s14, 0
	v_fma_f32 v154, v67, s14, 0
	v_max3_f32 v66, v155, s15, v154
	v_fma_f32 v153, v68, s14, 0
	v_fma_f32 v152, v69, s14, 0
	v_max3_f32 v66, v66, v153, v152
	v_fma_f32 v151, v70, s14, 0
	v_fma_f32 v150, v71, s14, 0
	v_max3_f32 v66, v66, v151, v150
	v_fma_f32 v149, v72, s14, 0
	v_fma_f32 v148, v73, s14, 0
	v_max3_f32 v66, v66, v149, v148
	v_fma_f32 v74, v74, s14, 0
	v_fma_f32 v73, v75, s14, 0
	v_max3_f32 v66, v66, v74, v73
	v_fma_f32 v72, v76, s14, 0
	v_fma_f32 v71, v77, s14, 0
	v_max3_f32 v66, v66, v72, v71
	v_fma_f32 v70, v78, s14, 0
	v_fma_f32 v69, v79, s14, 0
	v_max3_f32 v67, v66, v70, v69
	v_fma_f32 v68, v80, s14, 0
	v_fma_f32 v66, v81, s14, 0
	v_max3_f32 v67, v67, v68, v66
	v_mov_b32_e32 v75, v67
	s_nop 1
	v_permlane32_swap_b32_e32 v75, v67
	v_max_f32_e32 v67, v67, v75
	v_add_f32_e32 v75, 0x41000000, v145
	v_cmp_gt_f32_e32 vcc, v67, v75
	s_nop 1
	v_cndmask_b32_e32 v67, v145, v67, vcc
	s_cbranch_vccz .LBB0_251
	v_sub_f32_e32 v75, v145, v67
	v_exp_f32_e32 v76, v75
	v_mov_b32_e32 v145, v67
	v_mul_f32_e32 v147, v147, v76
	v_pk_mul_f32 v[64:65], v[64:65], v[76:77] op_sel_hi:[1,0]
	v_pk_mul_f32 v[62:63], v[62:63], v[76:77] op_sel_hi:[1,0]
	v_pk_mul_f32 v[60:61], v[60:61], v[76:77] op_sel_hi:[1,0]
	v_pk_mul_f32 v[58:59], v[58:59], v[76:77] op_sel_hi:[1,0]
	v_pk_mul_f32 v[56:57], v[56:57], v[76:77] op_sel_hi:[1,0]
	v_pk_mul_f32 v[54:55], v[54:55], v[76:77] op_sel_hi:[1,0]
	v_pk_mul_f32 v[52:53], v[52:53], v[76:77] op_sel_hi:[1,0]
	v_pk_mul_f32 v[50:51], v[50:51], v[76:77] op_sel_hi:[1,0]
	v_pk_mul_f32 v[48:49], v[48:49], v[76:77] op_sel_hi:[1,0]
	v_pk_mul_f32 v[46:47], v[46:47], v[76:77] op_sel_hi:[1,0]
	v_pk_mul_f32 v[44:45], v[44:45], v[76:77] op_sel_hi:[1,0]
	v_pk_mul_f32 v[42:43], v[42:43], v[76:77] op_sel_hi:[1,0]
	v_pk_mul_f32 v[40:41], v[40:41], v[76:77] op_sel_hi:[1,0]
	v_pk_mul_f32 v[38:39], v[38:39], v[76:77] op_sel_hi:[1,0]
	v_pk_mul_f32 v[36:37], v[36:37], v[76:77] op_sel_hi:[1,0]
	v_pk_mul_f32 v[34:35], v[34:35], v[76:77] op_sel_hi:[1,0]
	v_pk_mul_f32 v[32:33], v[32:33], v[76:77] op_sel_hi:[1,0]
	v_pk_mul_f32 v[30:31], v[30:31], v[76:77] op_sel_hi:[1,0]
	v_pk_mul_f32 v[28:29], v[28:29], v[76:77] op_sel_hi:[1,0]
	v_pk_mul_f32 v[26:27], v[26:27], v[76:77] op_sel_hi:[1,0]
	v_pk_mul_f32 v[24:25], v[24:25], v[76:77] op_sel_hi:[1,0]
	v_pk_mul_f32 v[22:23], v[22:23], v[76:77] op_sel_hi:[1,0]
	v_pk_mul_f32 v[20:21], v[20:21], v[76:77] op_sel_hi:[1,0]
	v_pk_mul_f32 v[18:19], v[18:19], v[76:77] op_sel_hi:[1,0]
	v_pk_mul_f32 v[16:17], v[16:17], v[76:77] op_sel_hi:[1,0]
	v_pk_mul_f32 v[14:15], v[14:15], v[76:77] op_sel_hi:[1,0]
	v_pk_mul_f32 v[12:13], v[12:13], v[76:77] op_sel_hi:[1,0]
	v_pk_mul_f32 v[10:11], v[10:11], v[76:77] op_sel_hi:[1,0]
	v_pk_mul_f32 v[8:9], v[8:9], v[76:77] op_sel_hi:[1,0]
	v_pk_mul_f32 v[6:7], v[6:7], v[76:77] op_sel_hi:[1,0]
	v_pk_mul_f32 v[4:5], v[4:5], v[76:77] op_sel_hi:[1,0]
	v_pk_mul_f32 v[2:3], v[2:3], v[76:77] op_sel_hi:[1,0]
; template <int D, int NM, int KSTR, int VSTR, bool QLDS, class BF> ...
;     ...
;         const LAS unsigned char* Kb = (m == 0 ? K0 : K1) + (32 * kk + r) * KSTR + h * 16;
;         v16f S;
; #pragma unroll
;         for (int i = 0; i < 16; ++i) S[i] = 0.f;
;         v8s kfa[D / 16];
; #pragma unroll
;         for (int ks = 0; ks < D / 16; ++ks) kfa[ks] = *(const LAS v8s*)(Kb + ks * 32);
;         __builtin_amdgcn_sched_barrier(0);
; #pragma unroll
;         for (int ks = 0; ks < D / 16; ++ks) { const v8s qf = QLDS ? *(const LAS v8s*)(qlds + (m * (D / 16) + ks) * 1024) : Q[m][ks]; S = MFMA32(kfa[ks], qf, S); }
;         __builtin_amdgcn_sched_barrier(0);
;         float tmax = NEGBIG;
; #pragma unroll
;         for (int i = 0; i < 16; ++i) { S[i] = S[i] * c1 + bias(i); tmax = fmaxf(tmax, S[i]); }
;         tmax = fmaxf(tmax, __shfl_xor(tmax, 32));
;         const float mo = st.m[m], mn = fmaxf(mo, tmax);
;         if (__any(mn > mo)) {
;             const float alpha = __builtin_amdgcn_exp2f(mo - mn);
;             st.l[m] *= alpha;
; #pragma unroll
;             for (int eb = 0; eb < 4; ++eb)
; #pragma unroll
;                 for (int i = 0; i < 16; ++i) st.O[m][eb][i] *= alpha;
;             st.m[m] = mn;
;         }
;         float ps = 0.f;
; #pragma unroll
;         for (int i = 0; i < 16; ++i) { S[i] = __builtin_amdgcn_exp2f(S[i] - mn); ps += S[i]; }
;         st.l[m] += ps;
; #pragma unroll
;         for (int s2 = 0; s2 < 2; ++s2) { v4u w; w.x = pk2(S[8 * s2 + 0], S[8 * s2 + 1]); w.y = pk2(S[8 * s2 + 2], S[8 * s2 + 3]); w.z = pk2(S[8 * s2 + 4], S[8 * s2 + 5]); w.w = pk2(S[8 * s2 + 6], S[8 * s2 + 7]);
;             P[m][s2] = __builtin_bit_cast(v8s, w); }
;     }
;     const int lane_ = h * 32 + r, q_ = (lane_ >> 2) & 3, p_ = lane_ & 3, g1_ = (lane_ >> 4) & 1;
;     const LAS unsigned char* vb0 = Vb + ((32 * kk + 4 * h + q_) * VSTR + (16 * g1_ + 4 * p_) * 2);
; #pragma unroll
;     for (int s2 = 0; s2 < 2; ++s2) {
;         const LAS unsigned char* va = vb0 + 16 * s2 * VSTR;
;         v8s vfa[4];
; #pragma unroll
;         for (int eb = 0; eb < 4; ++eb) {
;             const v4s lo = __builtin_amdgcn_ds_read_tr16_b64_v4i16((LAS v4s*)(va + 64 * eb)), hi = __builtin_amdgcn_ds_read_tr16_b64_v4i16((LAS v4s*)(va + 64 * eb + 8 * VSTR));
;             vfa[eb] = __builtin_shufflevector(lo, hi, 0, 1, 2, 3, 4, 5, 6, 7); }
;         __builtin_amdgcn_sched_barrier(0);
.LBB0_251:
	v_sub_f32_e32 v75, v155, v67
	v_exp_f32_e32 v75, v75
	v_sub_f32_e32 v77, v154, v67
	v_exp_f32_e32 v77, v77
	v_sub_f32_e32 v78, v153, v67
	v_exp_f32_e32 v78, v78
	v_sub_f32_e32 v79, v152, v67
	v_exp_f32_e32 v79, v79
	v_sub_f32_e32 v80, v151, v67
	v_add_f32_e32 v76, 0, v75
	v_exp_f32_e32 v80, v80
	v_sub_f32_e32 v81, v150, v67
	v_add_f32_e32 v76, v77, v76
	v_exp_f32_e32 v81, v81
	v_sub_f32_e32 v149, v149, v67
	v_add_f32_e32 v76, v78, v76
	v_exp_f32_e32 v149, v149
	v_sub_f32_e32 v148, v148, v67
	v_add_f32_e32 v76, v79, v76
	v_exp_f32_e32 v148, v148
	v_sub_f32_e32 v74, v74, v67
	v_add_f32_e32 v76, v80, v76
	v_exp_f32_e32 v74, v74
	v_sub_f32_e32 v73, v73, v67
	v_add_f32_e32 v76, v81, v76
	v_exp_f32_e32 v73, v73
	v_sub_f32_e32 v72, v72, v67
	v_add_f32_e32 v76, v149, v76
	v_exp_f32_e32 v72, v72
	v_sub_f32_e32 v71, v71, v67
	v_add_f32_e32 v76, v148, v76
	v_exp_f32_e32 v71, v71
	v_sub_f32_e32 v70, v70, v67
	v_add_f32_e32 v76, v74, v76
	v_exp_f32_e32 v150, v70
	v_add_f32_e32 v76, v73, v76
	v_add_f32_e32 v76, v72, v76
	v_add_f32_e32 v76, v71, v76
	v_sub_f32_e32 v69, v69, v67
	v_add_f32_e32 v70, v150, v76
	v_exp_f32_e32 v76, v69
	v_sub_f32_e32 v68, v68, v67
	v_exp_f32_e32 v151, v68
	v_sub_f32_e32 v66, v66, v67
	v_exp_f32_e32 v152, v66
	v_add_f32_e32 v69, v76, v70
	v_add_f32_e32 v68, v151, v69
	v_cvt_pk_bf16_f32 v67, v78, v79
	v_add_f32_e32 v66, v152, v68
	v_add_f32_e32 v147, v66, v147
	v_cvt_pk_bf16_f32 v66, v75, v77
	v_cvt_pk_bf16_f32 v68, v80, v81
	v_cvt_pk_bf16_f32 v69, v149, v148
	v_cvt_pk_bf16_f32 v70, v74, v73
	v_cvt_pk_bf16_f32 v71, v72, v71
	v_cvt_pk_bf16_f32 v72, v150, v76
	v_cvt_pk_bf16_f32 v73, v151, v152
	ds_read_b64_tr_b16 v[74:75], v143 offset:17408
	ds_read_b64_tr_b16 v[76:77], v143 offset:19968
	ds_read_b64_tr_b16 v[78:79], v143 offset:17472
	ds_read_b64_tr_b16 v[80:81], v143 offset:20032
	ds_read_b64_tr_b16 v[148:149], v143 offset:17536
	ds_read_b64_tr_b16 v[150:151], v143 offset:20096
	ds_read_b64_tr_b16 v[152:153], v143 offset:17600
	ds_read_b64_tr_b16 v[154:155], v143 offset:20160
	s_waitcnt lgkmcnt(6)
	v_mfma_f32_32x32x16_bf16 v[50:65], v[74:77], v[66:69], v[50:65]
	s_waitcnt lgkmcnt(4)
	v_mfma_f32_32x32x16_bf16 v[34:49], v[78:81], v[66:69], v[34:49]
	s_waitcnt lgkmcnt(2)
	v_mfma_f32_32x32x16_bf16 v[18:33], v[148:151], v[66:69], v[18:33]
	s_waitcnt lgkmcnt(0)
	v_mfma_f32_32x32x16_bf16 v[2:17], v[152:155], v[66:69], v[2:17]
	ds_read_b64_tr_b16 v[66:67], v143 offset:22528
	ds_read_b64_tr_b16 v[74:75], v143 offset:22592
	ds_read_b64_tr_b16 v[78:79], v143 offset:22656
	ds_read_b64_tr_b16 v[148:149], v143 offset:22720
	ds_read_b64_tr_b16 v[68:69], v143 offset:25088
	ds_read_b64_tr_b16 v[76:77], v143 offset:25152
	ds_read_b64_tr_b16 v[80:81], v143 offset:25216
	ds_read_b64_tr_b16 v[150:151], v143 offset:25280
	s_waitcnt lgkmcnt(3)
	v_mfma_f32_32x32x16_bf16 v[50:65], v[66:69], v[70:73], v[50:65]
	s_waitcnt lgkmcnt(2)
	v_mfma_f32_32x32x16_bf16 v[34:49], v[74:77], v[70:73], v[34:49]
	s_waitcnt lgkmcnt(1)
	v_mfma_f32_32x32x16_bf16 v[18:33], v[78:81], v[70:73], v[18:33]
	s_waitcnt lgkmcnt(0)
	v_mfma_f32_32x32x16_bf16 v[2:17], v[148:151], v[70:73], v[2:17]
	ds_read_b128 v[66:69], v144 offset:8704
	ds_read_b128 v[148:151], v144 offset:8736
	ds_read_b128 v[152:155], v144 offset:8768
	ds_read_b128 v[156:159], v144 offset:8800
	ds_read_b128 v[160:163], v144 offset:8832
	ds_read_b128 v[174:177], v144 offset:8864
	ds_read_b128 v[178:181], v144 offset:8896
	ds_read_b128 v[182:185], v144 offset:8928
	s_waitcnt lgkmcnt(7)
	v_mfma_f32_32x32x16_bf16 v[66:81], v[66:69], v[110:113], 0
	s_waitcnt lgkmcnt(6)
	v_mfma_f32_32x32x16_bf16 v[66:81], v[148:151], v[106:109], v[66:81]
	s_waitcnt lgkmcnt(5)
	v_mfma_f32_32x32x16_bf16 v[66:81], v[152:155], v[102:105], v[66:81]
	s_waitcnt lgkmcnt(4)
	v_mfma_f32_32x32x16_bf16 v[66:81], v[156:159], v[98:101], v[66:81]
	s_waitcnt lgkmcnt(3)
	v_mfma_f32_32x32x16_bf16 v[66:81], v[160:163], v[94:97], v[66:81]
	s_waitcnt lgkmcnt(2)
	v_mfma_f32_32x32x16_bf16 v[66:81], v[174:177], v[90:93], v[66:81]
	s_waitcnt lgkmcnt(1)
	v_mfma_f32_32x32x16_bf16 v[66:81], v[178:181], v[86:89], v[66:81]
	s_waitcnt lgkmcnt(0)
	v_mfma_f32_32x32x16_bf16 v[66:81], v[182:185], v[82:85], v[66:81]
	s_nop 11
	v_fma_f32 v155, v66, s14, 0
	v_fma_f32 v154, v67, s14, 0
	v_max3_f32 v66, v155, s15, v154
	v_fma_f32 v153, v68, s14, 0
	v_fma_f32 v152, v69, s14, 0
	v_max3_f32 v66, v66, v153, v152
	v_fma_f32 v151, v70, s14, 0
	v_fma_f32 v150, v71, s14, 0
	v_max3_f32 v66, v66, v151, v150
	v_fma_f32 v149, v72, s14, 0
	v_fma_f32 v148, v73, s14, 0
	v_max3_f32 v66, v66, v149, v148
	v_fma_f32 v74, v74, s14, 0
	v_fma_f32 v73, v75, s14, 0
	v_max3_f32 v66, v66, v74, v73
	v_fma_f32 v72, v76, s14, 0
	v_fma_f32 v71, v77, s14, 0
	v_max3_f32 v66, v66, v72, v71
	v_fma_f32 v70, v78, s14, 0
	v_fma_f32 v69, v79, s14, 0
	v_max3_f32 v67, v66, v70, v69
	v_fma_f32 v68, v80, s14, 0
	v_fma_f32 v66, v81, s14, 0
	v_max3_f32 v67, v67, v68, v66
	v_mov_b32_e32 v75, v67
	s_nop 1
	v_permlane32_swap_b32_e32 v75, v67
	v_max_f32_e32 v67, v67, v75
	v_add_f32_e32 v75, 0x41000000, v145
	v_cmp_gt_f32_e32 vcc, v67, v75
	s_nop 1
	v_cndmask_b32_e32 v67, v145, v67, vcc
	s_cbranch_vccz .LBB0_248
; #define LAS __attribute__((address_space(3)))
; #define MFMA32(a, b, c) __builtin_amdgcn_mfma_f32_32x32x16_bf16((a), (b), (c), 0, 0, 0)
; template <int D, int NM, int KSTR, int VSTR, bool QLDS, class BF> ...
;     ...
;         const LAS unsigned char* Kb = (m == 0 ? K0 : K1) + (32 * kk + r) * KSTR + h * 16;
;         v16f S;
; #pragma unroll
;         for (int i = 0; i < 16; ++i) S[i] = 0.f;
;         v8s kfa[D / 16];
; #pragma unroll
;         for (int ks = 0; ks < D / 16; ++ks) kfa[ks] = *(const LAS v8s*)(Kb + ks * 32);
;         __builtin_amdgcn_sched_barrier(0);
; #pragma unroll
;         for (int ks = 0; ks < D / 16; ++ks) { const v8s qf = QLDS ? *(const LAS v8s*)(qlds + (m * (D / 16) + ks) * 1024) : Q[m][ks]; S = MFMA32(kfa[ks], qf, S); }
;         __builtin_amdgcn_sched_barrier(0);
;         float tmax = NEGBIG;
; #pragma unroll
;         for (int i = 0; i < 16; ++i) { S[i] = S[i] * c1 + bias(i); tmax = fmaxf(tmax, S[i]); }
;         tmax = fmaxf(tmax, __shfl_xor(tmax, 32));
;         const float mo = st.m[m], mn = fmaxf(mo, tmax);
;         if (__any(mn > mo)) {
;             const float alpha = __builtin_amdgcn_exp2f(mo - mn);
;             st.l[m] *= alpha;
; #pragma unroll
;             for (int eb = 0; eb < 4; ++eb)
; #pragma unroll
;                 for (int i = 0; i < 16; ++i) st.O[m][eb][i] *= alpha;
;             st.m[m] = mn;
;         }
; __device__ __forceinline__ void mem_item(const Params& p, LAS unsigned char* lds, const int item, const int layer) {
;     ...
;         __syncthreads();
;         *(LAS v4u*)dK = g0; *(LAS v4u*)(dK + 32 * 272) = g1; *(LAS v4u*)dV = g2; *(LAS v4u*)(dV + 32 * 320) = g3;
;         __syncthreads();
	v_sub_f32_e32 v75, v145, v67
	v_exp_f32_e32 v76, v75
	v_mov_b32_e32 v145, v67
	v_mul_f32_e32 v147, v147, v76
	v_pk_mul_f32 v[64:65], v[64:65], v[76:77] op_sel_hi:[1,0]
	v_pk_mul_f32 v[62:63], v[62:63], v[76:77] op_sel_hi:[1,0]
	v_pk_mul_f32 v[60:61], v[60:61], v[76:77] op_sel_hi:[1,0]
	v_pk_mul_f32 v[58:59], v[58:59], v[76:77] op_sel_hi:[1,0]
	v_pk_mul_f32 v[56:57], v[56:57], v[76:77] op_sel_hi:[1,0]
	v_pk_mul_f32 v[54:55], v[54:55], v[76:77] op_sel_hi:[1,0]
	v_pk_mul_f32 v[52:53], v[52:53], v[76:77] op_sel_hi:[1,0]
	v_pk_mul_f32 v[50:51], v[50:51], v[76:77] op_sel_hi:[1,0]
	v_pk_mul_f32 v[48:49], v[48:49], v[76:77] op_sel_hi:[1,0]
	v_pk_mul_f32 v[46:47], v[46:47], v[76:77] op_sel_hi:[1,0]
	v_pk_mul_f32 v[44:45], v[44:45], v[76:77] op_sel_hi:[1,0]
	v_pk_mul_f32 v[42:43], v[42:43], v[76:77] op_sel_hi:[1,0]
	v_pk_mul_f32 v[40:41], v[40:41], v[76:77] op_sel_hi:[1,0]
	v_pk_mul_f32 v[38:39], v[38:39], v[76:77] op_sel_hi:[1,0]
	v_pk_mul_f32 v[36:37], v[36:37], v[76:77] op_sel_hi:[1,0]
	v_pk_mul_f32 v[34:35], v[34:35], v[76:77] op_sel_hi:[1,0]
	v_pk_mul_f32 v[32:33], v[32:33], v[76:77] op_sel_hi:[1,0]
	v_pk_mul_f32 v[30:31], v[30:31], v[76:77] op_sel_hi:[1,0]
	v_pk_mul_f32 v[28:29], v[28:29], v[76:77] op_sel_hi:[1,0]
	v_pk_mul_f32 v[26:27], v[26:27], v[76:77] op_sel_hi:[1,0]
	v_pk_mul_f32 v[24:25], v[24:25], v[76:77] op_sel_hi:[1,0]
	v_pk_mul_f32 v[22:23], v[22:23], v[76:77] op_sel_hi:[1,0]
	v_pk_mul_f32 v[20:21], v[20:21], v[76:77] op_sel_hi:[1,0]
	v_pk_mul_f32 v[18:19], v[18:19], v[76:77] op_sel_hi:[1,0]
	v_pk_mul_f32 v[16:17], v[16:17], v[76:77] op_sel_hi:[1,0]
	v_pk_mul_f32 v[14:15], v[14:15], v[76:77] op_sel_hi:[1,0]
	v_pk_mul_f32 v[12:13], v[12:13], v[76:77] op_sel_hi:[1,0]
	v_pk_mul_f32 v[10:11], v[10:11], v[76:77] op_sel_hi:[1,0]
	v_pk_mul_f32 v[8:9], v[8:9], v[76:77] op_sel_hi:[1,0]
	v_pk_mul_f32 v[6:7], v[6:7], v[76:77] op_sel_hi:[1,0]
	v_pk_mul_f32 v[4:5], v[4:5], v[76:77] op_sel_hi:[1,0]
	v_pk_mul_f32 v[2:3], v[2:3], v[76:77] op_sel_hi:[1,0]
	s_branch .LBB0_248
.LBB0_253:
	s_barrier
	s_waitcnt vmcnt(3)
	ds_write_b128 v0, v[114:117]
	s_waitcnt vmcnt(1)
	ds_write_b128 v0, v[126:129] offset:8704
	ds_write_b128 v146, v[118:121] offset:17408
	s_waitcnt vmcnt(0)
	ds_write_b128 v146, v[122:125] offset:27648
	s_waitcnt lgkmcnt(0)
	s_barrier
	ds_read_b128 v[66:69], v144
	ds_read_b128 v[114:117], v144 offset:32
	ds_read_b128 v[118:121], v144 offset:64
	ds_read_b128 v[122:125], v144 offset:96
	ds_read_b128 v[126:129], v144 offset:128
	ds_read_b128 v[148:151], v144 offset:160
	ds_read_b128 v[152:155], v144 offset:192
	ds_read_b128 v[156:159], v144 offset:224
	s_waitcnt lgkmcnt(7)
	v_mfma_f32_32x32x16_bf16 v[66:81], v[66:69], v[110:113], 0
	s_waitcnt lgkmcnt(6)
	v_mfma_f32_32x32x16_bf16 v[66:81], v[114:117], v[106:109], v[66:81]
	s_waitcnt lgkmcnt(5)
	v_mfma_f32_32x32x16_bf16 v[66:81], v[118:121], v[102:105], v[66:81]
	s_waitcnt lgkmcnt(4)
	v_mfma_f32_32x32x16_bf16 v[66:81], v[122:125], v[98:101], v[66:81]
	s_waitcnt lgkmcnt(3)
	v_mfma_f32_32x32x16_bf16 v[66:81], v[126:129], v[94:97], v[66:81]
	s_waitcnt lgkmcnt(2)
	v_mfma_f32_32x32x16_bf16 v[66:81], v[148:151], v[90:93], v[66:81]
	s_waitcnt lgkmcnt(1)
	v_mfma_f32_32x32x16_bf16 v[66:81], v[152:155], v[86:89], v[66:81]
	s_waitcnt lgkmcnt(0)
	v_mfma_f32_32x32x16_bf16 v[66:81], v[156:159], v[82:85], v[66:81]
	s_nop 11
	v_fma_f32 v121, v66, s14, 0
	v_fma_f32 v120, v67, s14, 0
	v_max3_f32 v0, v121, s15, v120
	v_fma_f32 v119, v68, s14, 0
	v_fma_f32 v118, v69, s14, 0
	v_max3_f32 v0, v0, v119, v118
	v_fma_f32 v117, v70, s14, 0
	v_fma_f32 v116, v71, s14, 0
	v_max3_f32 v0, v0, v117, v116
	v_fma_f32 v115, v72, s14, 0
	v_fma_f32 v114, v73, s14, 0
	v_max3_f32 v0, v0, v115, v114
	v_fma_f32 v73, v74, s14, 0
	v_fma_f32 v72, v75, s14, 0
	v_max3_f32 v0, v0, v73, v72
	v_fma_f32 v71, v76, s14, 0
	v_fma_f32 v70, v77, s14, 0
	v_max3_f32 v0, v0, v71, v70
	v_fma_f32 v69, v78, s14, 0
	v_fma_f32 v68, v79, s14, 0
	v_max3_f32 v66, v0, v69, v68
	v_fma_f32 v67, v80, s14, 0
	v_fma_f32 v0, v81, s14, 0
	v_max3_f32 v66, v66, v67, v0
	v_mov_b32_e32 v74, v66
	s_nop 1
	v_permlane32_swap_b32_e32 v74, v66
	v_max_f32_e32 v66, v66, v74
	v_add_f32_e32 v74, 0x41000000, v145
	v_cmp_gt_f32_e32 vcc, v66, v74
	s_nop 1
	v_cndmask_b32_e32 v66, v145, v66, vcc
	s_cbranch_vccz .LBB0_255
	v_sub_f32_e32 v74, v145, v66
	v_exp_f32_e32 v74, v74
	v_mov_b32_e32 v145, v66
	v_mul_f32_e32 v147, v147, v74
	v_pk_mul_f32 v[64:65], v[64:65], v[74:75] op_sel_hi:[1,0]
	v_pk_mul_f32 v[62:63], v[62:63], v[74:75] op_sel_hi:[1,0]
	v_pk_mul_f32 v[60:61], v[60:61], v[74:75] op_sel_hi:[1,0]
	v_pk_mul_f32 v[58:59], v[58:59], v[74:75] op_sel_hi:[1,0]
	v_pk_mul_f32 v[56:57], v[56:57], v[74:75] op_sel_hi:[1,0]
	v_pk_mul_f32 v[54:55], v[54:55], v[74:75] op_sel_hi:[1,0]
	v_pk_mul_f32 v[52:53], v[52:53], v[74:75] op_sel_hi:[1,0]
	v_pk_mul_f32 v[50:51], v[50:51], v[74:75] op_sel_hi:[1,0]
	v_pk_mul_f32 v[48:49], v[48:49], v[74:75] op_sel_hi:[1,0]
	v_pk_mul_f32 v[46:47], v[46:47], v[74:75] op_sel_hi:[1,0]
	v_pk_mul_f32 v[44:45], v[44:45], v[74:75] op_sel_hi:[1,0]
	v_pk_mul_f32 v[42:43], v[42:43], v[74:75] op_sel_hi:[1,0]
	v_pk_mul_f32 v[40:41], v[40:41], v[74:75] op_sel_hi:[1,0]
	v_pk_mul_f32 v[38:39], v[38:39], v[74:75] op_sel_hi:[1,0]
	v_pk_mul_f32 v[36:37], v[36:37], v[74:75] op_sel_hi:[1,0]
	v_pk_mul_f32 v[34:35], v[34:35], v[74:75] op_sel_hi:[1,0]
	v_pk_mul_f32 v[32:33], v[32:33], v[74:75] op_sel_hi:[1,0]
	v_pk_mul_f32 v[30:31], v[30:31], v[74:75] op_sel_hi:[1,0]
	v_pk_mul_f32 v[28:29], v[28:29], v[74:75] op_sel_hi:[1,0]
	v_pk_mul_f32 v[26:27], v[26:27], v[74:75] op_sel_hi:[1,0]
	v_pk_mul_f32 v[24:25], v[24:25], v[74:75] op_sel_hi:[1,0]
	v_pk_mul_f32 v[22:23], v[22:23], v[74:75] op_sel_hi:[1,0]
	v_pk_mul_f32 v[20:21], v[20:21], v[74:75] op_sel_hi:[1,0]
	v_pk_mul_f32 v[18:19], v[18:19], v[74:75] op_sel_hi:[1,0]
	v_pk_mul_f32 v[16:17], v[16:17], v[74:75] op_sel_hi:[1,0]
	v_pk_mul_f32 v[14:15], v[14:15], v[74:75] op_sel_hi:[1,0]
	v_pk_mul_f32 v[12:13], v[12:13], v[74:75] op_sel_hi:[1,0]
	v_pk_mul_f32 v[10:11], v[10:11], v[74:75] op_sel_hi:[1,0]
	v_pk_mul_f32 v[8:9], v[8:9], v[74:75] op_sel_hi:[1,0]
	v_pk_mul_f32 v[6:7], v[6:7], v[74:75] op_sel_hi:[1,0]
	v_pk_mul_f32 v[4:5], v[4:5], v[74:75] op_sel_hi:[1,0]
	v_pk_mul_f32 v[2:3], v[2:3], v[74:75] op_sel_hi:[1,0]
; template <int D, int NM, int KSTR, int VSTR, bool QLDS, class BF> ...
;     ...
;         const LAS unsigned char* Kb = (m == 0 ? K0 : K1) + (32 * kk + r) * KSTR + h * 16;
;         v16f S;
; #pragma unroll
;         for (int i = 0; i < 16; ++i) S[i] = 0.f;
;         v8s kfa[D / 16];
; #pragma unroll
;         for (int ks = 0; ks < D / 16; ++ks) kfa[ks] = *(const LAS v8s*)(Kb + ks * 32);
;         __builtin_amdgcn_sched_barrier(0);
; #pragma unroll
;         for (int ks = 0; ks < D / 16; ++ks) { const v8s qf = QLDS ? *(const LAS v8s*)(qlds + (m * (D / 16) + ks) * 1024) : Q[m][ks]; S = MFMA32(kfa[ks], qf, S); }
;         __builtin_amdgcn_sched_barrier(0);
;         float tmax = NEGBIG;
; #pragma unroll
;         for (int i = 0; i < 16; ++i) { S[i] = S[i] * c1 + bias(i); tmax = fmaxf(tmax, S[i]); }
;         tmax = fmaxf(tmax, __shfl_xor(tmax, 32));
;         const float mo = st.m[m], mn = fmaxf(mo, tmax);
;         if (__any(mn > mo)) {
;             const float alpha = __builtin_amdgcn_exp2f(mo - mn);
;             st.l[m] *= alpha;
; #pragma unroll
;             for (int eb = 0; eb < 4; ++eb)
; #pragma unroll
;                 for (int i = 0; i < 16; ++i) st.O[m][eb][i] *= alpha;
;             st.m[m] = mn;
;         }
;         float ps = 0.f;
; #pragma unroll
;         for (int i = 0; i < 16; ++i) { S[i] = __builtin_amdgcn_exp2f(S[i] - mn); ps += S[i]; }
;         st.l[m] += ps;
; #pragma unroll
;         for (int s2 = 0; s2 < 2; ++s2) { v4u w; w.x = pk2(S[8 * s2 + 0], S[8 * s2 + 1]); w.y = pk2(S[8 * s2 + 2], S[8 * s2 + 3]); w.z = pk2(S[8 * s2 + 4], S[8 * s2 + 5]); w.w = pk2(S[8 * s2 + 6], S[8 * s2 + 7]);
;             P[m][s2] = __builtin_bit_cast(v8s, w); }
;     }
;     const int lane_ = h * 32 + r, q_ = (lane_ >> 2) & 3, p_ = lane_ & 3, g1_ = (lane_ >> 4) & 1;
;     const LAS unsigned char* vb0 = Vb + ((32 * kk + 4 * h + q_) * VSTR + (16 * g1_ + 4 * p_) * 2);
; #pragma unroll
;     for (int s2 = 0; s2 < 2; ++s2) {
;         const LAS unsigned char* va = vb0 + 16 * s2 * VSTR;
;         v8s vfa[4];
; #pragma unroll
;         for (int eb = 0; eb < 4; ++eb) {
;             const v4s lo = __builtin_amdgcn_ds_read_tr16_b64_v4i16((LAS v4s*)(va + 64 * eb)), hi = __builtin_amdgcn_ds_read_tr16_b64_v4i16((LAS v4s*)(va + 64 * eb + 8 * VSTR));
;             vfa[eb] = __builtin_shufflevector(lo, hi, 0, 1, 2, 3, 4, 5, 6, 7); }
;         __builtin_amdgcn_sched_barrier(0);
.LBB0_255:
	v_sub_f32_e32 v74, v121, v66
	v_exp_f32_e32 v74, v74
	v_sub_f32_e32 v76, v120, v66
	v_exp_f32_e32 v76, v76
	v_sub_f32_e32 v77, v119, v66
	v_exp_f32_e32 v77, v77
	v_sub_f32_e32 v78, v118, v66
	v_exp_f32_e32 v78, v78
	v_sub_f32_e32 v79, v117, v66
	v_add_f32_e32 v75, 0, v74
	v_exp_f32_e32 v79, v79
	v_sub_f32_e32 v80, v116, v66
	v_add_f32_e32 v75, v76, v75
	v_exp_f32_e32 v80, v80
	v_sub_f32_e32 v81, v115, v66
	v_add_f32_e32 v75, v77, v75
	v_exp_f32_e32 v81, v81
	v_sub_f32_e32 v114, v114, v66
	v_add_f32_e32 v75, v78, v75
	v_exp_f32_e32 v114, v114
	v_sub_f32_e32 v73, v73, v66
	v_add_f32_e32 v75, v79, v75
	v_exp_f32_e32 v73, v73
	v_sub_f32_e32 v72, v72, v66
	v_add_f32_e32 v75, v80, v75
	v_exp_f32_e32 v72, v72
	v_sub_f32_e32 v71, v71, v66
	v_add_f32_e32 v75, v81, v75
	v_exp_f32_e32 v71, v71
	v_sub_f32_e32 v70, v70, v66
	v_add_f32_e32 v75, v114, v75
	v_exp_f32_e32 v115, v70
	v_add_f32_e32 v75, v73, v75
	v_add_f32_e32 v75, v72, v75
	v_add_f32_e32 v75, v71, v75
	v_sub_f32_e32 v69, v69, v66
	v_add_f32_e32 v70, v115, v75
	v_exp_f32_e32 v75, v69
	v_sub_f32_e32 v68, v68, v66
	v_exp_f32_e32 v116, v68
	v_sub_f32_e32 v67, v67, v66
	v_exp_f32_e32 v117, v67
	v_sub_f32_e32 v0, v0, v66
	v_exp_f32_e32 v118, v0
	v_add_f32_e32 v69, v75, v70
	v_add_f32_e32 v68, v116, v69
	v_add_f32_e32 v67, v117, v68
	v_add_f32_e32 v0, v118, v67
	v_cvt_pk_bf16_f32 v66, v74, v76
	v_cvt_pk_bf16_f32 v67, v77, v78
	v_cvt_pk_bf16_f32 v68, v79, v80
	v_cvt_pk_bf16_f32 v69, v81, v114
	v_cvt_pk_bf16_f32 v70, v73, v72
	v_cvt_pk_bf16_f32 v71, v71, v115
	v_cvt_pk_bf16_f32 v72, v75, v116
	v_cvt_pk_bf16_f32 v73, v117, v118
	ds_read_b64_tr_b16 v[74:75], v143 offset:17408
	ds_read_b64_tr_b16 v[76:77], v143 offset:19968
	ds_read_b64_tr_b16 v[78:79], v143 offset:17472
	ds_read_b64_tr_b16 v[80:81], v143 offset:20032
	ds_read_b64_tr_b16 v[114:115], v143 offset:17536
	ds_read_b64_tr_b16 v[116:117], v143 offset:20096
	ds_read_b64_tr_b16 v[118:119], v143 offset:17600
	ds_read_b64_tr_b16 v[120:121], v143 offset:20160
	v_add_f32_e32 v0, v0, v147
	s_waitcnt lgkmcnt(6)
	v_mfma_f32_32x32x16_bf16 v[50:65], v[74:77], v[66:69], v[50:65]
	s_waitcnt lgkmcnt(4)
	v_mfma_f32_32x32x16_bf16 v[34:49], v[78:81], v[66:69], v[34:49]
	s_waitcnt lgkmcnt(2)
	v_mfma_f32_32x32x16_bf16 v[18:33], v[114:117], v[66:69], v[18:33]
	s_waitcnt lgkmcnt(0)
	v_mfma_f32_32x32x16_bf16 v[2:17], v[118:121], v[66:69], v[2:17]
	ds_read_b64_tr_b16 v[66:67], v143 offset:22528
	ds_read_b64_tr_b16 v[74:75], v143 offset:22592
	ds_read_b64_tr_b16 v[78:79], v143 offset:22656
	ds_read_b64_tr_b16 v[114:115], v143 offset:22720
	ds_read_b64_tr_b16 v[68:69], v143 offset:25088
	ds_read_b64_tr_b16 v[76:77], v143 offset:25152
	ds_read_b64_tr_b16 v[80:81], v143 offset:25216
	ds_read_b64_tr_b16 v[116:117], v143 offset:25280
	s_waitcnt lgkmcnt(3)
	v_mfma_f32_32x32x16_bf16 v[50:65], v[66:69], v[70:73], v[50:65]
	s_waitcnt lgkmcnt(2)
	v_mfma_f32_32x32x16_bf16 v[34:49], v[74:77], v[70:73], v[34:49]
	s_waitcnt lgkmcnt(1)
	v_mfma_f32_32x32x16_bf16 v[18:33], v[78:81], v[70:73], v[18:33]
	s_waitcnt lgkmcnt(0)
	v_mfma_f32_32x32x16_bf16 v[2:17], v[114:117], v[70:73], v[2:17]
	ds_read_b128 v[66:69], v144 offset:8704
	ds_read_b128 v[114:117], v144 offset:8736
	ds_read_b128 v[118:121], v144 offset:8768
	ds_read_b128 v[122:125], v144 offset:8800
	ds_read_b128 v[126:129], v144 offset:8832
	ds_read_b128 v[146:149], v144 offset:8864
	ds_read_b128 v[150:153], v144 offset:8896
	ds_read_b128 v[154:157], v144 offset:8928
	s_waitcnt lgkmcnt(7)
	v_mfma_f32_32x32x16_bf16 v[66:81], v[66:69], v[110:113], 0
	s_waitcnt lgkmcnt(6)
	v_mfma_f32_32x32x16_bf16 v[66:81], v[114:117], v[106:109], v[66:81]
	s_waitcnt lgkmcnt(5)
	v_mfma_f32_32x32x16_bf16 v[66:81], v[118:121], v[102:105], v[66:81]
	s_waitcnt lgkmcnt(4)
	v_mfma_f32_32x32x16_bf16 v[66:81], v[122:125], v[98:101], v[66:81]
	s_waitcnt lgkmcnt(3)
	v_mfma_f32_32x32x16_bf16 v[66:81], v[126:129], v[94:97], v[66:81]
	s_waitcnt lgkmcnt(2)
	v_mfma_f32_32x32x16_bf16 v[66:81], v[146:149], v[90:93], v[66:81]
	s_waitcnt lgkmcnt(1)
	v_mfma_f32_32x32x16_bf16 v[66:81], v[150:153], v[86:89], v[66:81]
	s_waitcnt lgkmcnt(0)
	v_mfma_f32_32x32x16_bf16 v[66:81], v[154:157], v[82:85], v[66:81]
	s_nop 11
	v_fma_f32 v89, v66, s14, 0
	v_fma_f32 v88, v67, s14, 0
	v_max3_f32 v66, v89, s15, v88
	v_fma_f32 v87, v68, s14, 0
	v_fma_f32 v86, v69, s14, 0
	v_max3_f32 v66, v66, v87, v86
	v_fma_f32 v85, v70, s14, 0
	v_fma_f32 v84, v71, s14, 0
	v_max3_f32 v66, v66, v85, v84
	v_fma_f32 v83, v72, s14, 0
	v_fma_f32 v82, v73, s14, 0
	v_max3_f32 v66, v66, v83, v82
	v_fma_f32 v74, v74, s14, 0
	v_fma_f32 v73, v75, s14, 0
	v_max3_f32 v66, v66, v74, v73
	v_fma_f32 v72, v76, s14, 0
	v_fma_f32 v71, v77, s14, 0
	v_max3_f32 v66, v66, v72, v71
	v_fma_f32 v70, v78, s14, 0
	v_fma_f32 v69, v79, s14, 0
	v_max3_f32 v67, v66, v70, v69
	v_fma_f32 v68, v80, s14, 0
	v_fma_f32 v66, v81, s14, 0
	v_max3_f32 v67, v67, v68, v66
	v_mov_b32_e32 v75, v67
	s_nop 1
	v_permlane32_swap_b32_e32 v75, v67
	v_max_f32_e32 v67, v67, v75
	v_add_f32_e32 v75, 0x41000000, v145
	v_cmp_gt_f32_e32 vcc, v67, v75
	s_nop 1
	v_cndmask_b32_e32 v67, v145, v67, vcc
	s_cbranch_vccz .LBB0_154
; template <int D, int NM, int KSTR, int VSTR, bool QLDS, class BF> ...
;     ...
;         if (__any(mn > mo)) {
;             const float alpha = __builtin_amdgcn_exp2f(mo - mn);
;             st.l[m] *= alpha;
; #pragma unroll
;             for (int eb = 0; eb < 4; ++eb)
; #pragma unroll
;                 for (int i = 0; i < 16; ++i) st.O[m][eb][i] *= alpha;
;             st.m[m] = mn;
;         }
	v_sub_f32_e32 v75, v145, v67
	v_exp_f32_e32 v76, v75
	s_nop 0
	v_mul_f32_e32 v0, v0, v76
	v_pk_mul_f32 v[64:65], v[64:65], v[76:77] op_sel_hi:[1,0]
	v_pk_mul_f32 v[62:63], v[62:63], v[76:77] op_sel_hi:[1,0]
	v_pk_mul_f32 v[60:61], v[60:61], v[76:77] op_sel_hi:[1,0]
	v_pk_mul_f32 v[58:59], v[58:59], v[76:77] op_sel_hi:[1,0]
	v_pk_mul_f32 v[56:57], v[56:57], v[76:77] op_sel_hi:[1,0]
	v_pk_mul_f32 v[54:55], v[54:55], v[76:77] op_sel_hi:[1,0]
	v_pk_mul_f32 v[52:53], v[52:53], v[76:77] op_sel_hi:[1,0]
	v_pk_mul_f32 v[50:51], v[50:51], v[76:77] op_sel_hi:[1,0]
	v_pk_mul_f32 v[48:49], v[48:49], v[76:77] op_sel_hi:[1,0]
	v_pk_mul_f32 v[46:47], v[46:47], v[76:77] op_sel_hi:[1,0]
	v_pk_mul_f32 v[44:45], v[44:45], v[76:77] op_sel_hi:[1,0]
	v_pk_mul_f32 v[42:43], v[42:43], v[76:77] op_sel_hi:[1,0]
	v_pk_mul_f32 v[40:41], v[40:41], v[76:77] op_sel_hi:[1,0]
	v_pk_mul_f32 v[38:39], v[38:39], v[76:77] op_sel_hi:[1,0]
	v_pk_mul_f32 v[36:37], v[36:37], v[76:77] op_sel_hi:[1,0]
	v_pk_mul_f32 v[34:35], v[34:35], v[76:77] op_sel_hi:[1,0]
	v_pk_mul_f32 v[32:33], v[32:33], v[76:77] op_sel_hi:[1,0]
	v_pk_mul_f32 v[30:31], v[30:31], v[76:77] op_sel_hi:[1,0]
	v_pk_mul_f32 v[28:29], v[28:29], v[76:77] op_sel_hi:[1,0]
	v_pk_mul_f32 v[26:27], v[26:27], v[76:77] op_sel_hi:[1,0]
	v_pk_mul_f32 v[24:25], v[24:25], v[76:77] op_sel_hi:[1,0]
	v_pk_mul_f32 v[22:23], v[22:23], v[76:77] op_sel_hi:[1,0]
	v_pk_mul_f32 v[20:21], v[20:21], v[76:77] op_sel_hi:[1,0]
	v_pk_mul_f32 v[18:19], v[18:19], v[76:77] op_sel_hi:[1,0]
	v_pk_mul_f32 v[16:17], v[16:17], v[76:77] op_sel_hi:[1,0]
	v_pk_mul_f32 v[14:15], v[14:15], v[76:77] op_sel_hi:[1,0]
	v_pk_mul_f32 v[12:13], v[12:13], v[76:77] op_sel_hi:[1,0]
	v_pk_mul_f32 v[10:11], v[10:11], v[76:77] op_sel_hi:[1,0]
	v_pk_mul_f32 v[8:9], v[8:9], v[76:77] op_sel_hi:[1,0]
	v_pk_mul_f32 v[6:7], v[6:7], v[76:77] op_sel_hi:[1,0]
	v_pk_mul_f32 v[4:5], v[4:5], v[76:77] op_sel_hi:[1,0]
	v_pk_mul_f32 v[2:3], v[2:3], v[76:77] op_sel_hi:[1,0]
	s_branch .LBB0_154
